# generation bump of the XCD leader no longer waited for at sites a-d (all later generation compares monotonic)
# speedup vs baseline: 1.0101x; 1.0007x over previous
.Lgb_d:
	v_readlane_b32 s2, v252, 49
	v_readlane_b32 s3, v252, 50
	s_waitcnt vmcnt(0)
	buffer_inv sc1
	s_nop 2
	global_atomic_add v197, v223, s[2:3]
.LBB0_125:
	s_or_b64 exec, exec, s[6:7]
	s_waitcnt lgkmcnt(0)
	s_barrier

.Lgb_a:
	v_readlane_b32 s2, v252, 49
	v_readlane_b32 s3, v252, 50
	s_waitcnt vmcnt(0)
	buffer_inv sc1
	s_nop 2
	global_atomic_add v197, v223, s[2:3]
.LBB0_617:
	s_or_b64 exec, exec, s[6:7]
	s_waitcnt lgkmcnt(0)
	s_barrier

.Lgb_b:
	v_readlane_b32 s2, v252, 49
	v_readlane_b32 s3, v252, 50
	s_waitcnt vmcnt(0)
	buffer_inv sc1
	s_nop 2
	global_atomic_add v197, v223, s[2:3]
.LBB0_671:
	s_or_b64 exec, exec, s[6:7]
	s_waitcnt lgkmcnt(0)
	s_barrier

.LBB0_800:
	v_readlane_b32 s2, v252, 47
	v_readlane_b32 s3, v252, 48
	v_cvt_f32_u32_e32 v1, v2
	v_sub_u32_e32 v4, 0, v2
	v_rcp_iflag_f32_e32 v1, v1
	s_nop 1
	global_atomic_add v3, v197, v223, s[2:3] sc0
	v_mul_f32_e32 v1, 0x4f7ffffe, v1
	v_cvt_u32_f32_e32 v1, v1
	v_mul_lo_u32 v4, v4, v1
	v_mul_hi_u32 v4, v1, v4
	v_add_u32_e32 v1, v1, v4
	s_waitcnt vmcnt(0)
	v_mul_hi_u32 v1, v3, v1
	v_mul_lo_u32 v4, v1, v2
	v_sub_u32_e32 v4, v3, v4
	v_add_u32_e32 v5, 1, v1
	v_cmp_ge_u32_e32 vcc, v4, v2
	v_add_u32_e32 v3, 1, v3
	s_nop 0
	v_cndmask_b32_e32 v1, v1, v5, vcc
	v_sub_u32_e32 v5, v4, v2
	v_cndmask_b32_e32 v4, v4, v5, vcc
	v_add_u32_e32 v5, 1, v1
	v_cmp_ge_u32_e32 vcc, v4, v2
	s_nop 1
	v_cndmask_b32_e32 v1, v1, v5, vcc
	v_mul_lo_u32 v4, v2, v1
	v_add_u32_e32 v2, v4, v2
	v_cmp_ne_u32_e32 vcc, v3, v2
	s_and_saveexec_b64 s[2:3], vcc
	s_xor_b64 s[8:9], exec, s[2:3]
	s_cbranch_execz .LBB0_814
	buffer_inv sc1
	v_readlane_b32 s2, v252, 49
	v_readlane_b32 s3, v252, 50
	s_waitcnt lgkmcnt(0)
	s_nop 3
	global_load_dword v0, v197, s[2:3] sc1
	s_waitcnt vmcnt(0)
	v_cmp_le_u32_e32 vcc, v0, v1
	s_and_saveexec_b64 s[12:13], vcc
	s_cbranch_execz .LBB0_813
	s_mov_b32 s26, s30
	s_mov_b32 s1, 1
	s_mov_b64 s[18:19], 0
	s_branch .LBB0_804

.LBB0_806:
	v_readlane_b32 s2, v252, 49
	v_readlane_b32 s3, v252, 50
	s_add_i32 s1, s1, 1
	s_mov_b64 s[24:25], -1
	s_nop 2
	global_load_dword v0, v197, s[2:3] sc1
	s_waitcnt vmcnt(0)
	v_cmp_gt_u32_e32 vcc, v0, v1
	s_orn2_b64 s[22:23], vcc, exec
	s_branch .LBB0_803

.LBB0_831:
	s_or_b64 exec, exec, s[8:9]
	v_readlane_b32 s2, v252, 49
	v_readlane_b32 s3, v252, 50
	s_waitcnt vmcnt(0)
	buffer_inv sc1
	s_nop 2
	global_atomic_add v197, v223, s[2:3]
.LBB0_832:
	s_or_b64 exec, exec, s[6:7]
	s_waitcnt lgkmcnt(0)
	s_barrier
